# NSA importance reduction: xor-1/xor-2 lane exchanges as DPP quad_perm adds instead of ds_bpermute round trips
# speedup vs baseline: 1.0615x; 1.0126x over previous
.LBB0_85:
	s_or_b64 exec, exec, s[0:1]
	v_add_f32_e32 v130, v130, v131
	v_add_f32_e32 v128, v128, v129
	v_cndmask_b32_e64 v132, v150, v151, s[74:75]
	v_add_f32_e32 v128, v128, v130
	v_add_f32_e32 v128, v128, v132
	s_waitcnt lgkmcnt(0)
	s_nop 0
	v_add_f32_dpp v128, v128, v128 quad_perm:[1,0,3,2] row_mask:0xf bank_mask:0xf
	s_nop 1
	v_add_f32_dpp v128, v128, v128 quad_perm:[2,3,0,1] row_mask:0xf bank_mask:0xf
	s_and_saveexec_b64 s[0:1], s[12:13]
	s_cbranch_execz .LBB0_87
	v_cmp_eq_u32_e32 vcc, s89, v178
	v_cmp_eq_u32_e64 s[78:79], s3, v178
	v_cmp_ge_i32_e64 s[80:81], s89, v178
	s_or_b64 vcc, vcc, s[78:79]
	s_nop 0
	v_cndmask_b32_e64 v128, v252, v128, s[80:81]
	v_cndmask_b32_e32 v128, v128, v204, vcc
	ds_write_b32 v177, v128 offset:8
.LBB0_87:
	s_or_b64 exec, exec, s[0:1]
	v_add_f32_e32 v126, v126, v127
	v_add_f32_e32 v124, v124, v125
	v_cndmask_b32_e64 v128, v149, v150, s[74:75]
	v_add_f32_e32 v124, v124, v126
	v_add_f32_e32 v124, v124, v128
	s_waitcnt lgkmcnt(0)
	s_nop 0
	v_add_f32_dpp v124, v124, v124 quad_perm:[1,0,3,2] row_mask:0xf bank_mask:0xf
	s_nop 1
	v_add_f32_dpp v124, v124, v124 quad_perm:[2,3,0,1] row_mask:0xf bank_mask:0xf
	s_and_saveexec_b64 s[0:1], s[12:13]
	s_cbranch_execz .LBB0_89
	v_cmp_eq_u32_e32 vcc, s89, v179
	v_cmp_eq_u32_e64 s[78:79], s3, v179
	v_cmp_ge_i32_e64 s[80:81], s89, v179
	s_or_b64 vcc, vcc, s[78:79]
	s_nop 0
	v_cndmask_b32_e64 v124, v252, v124, s[80:81]
	v_cndmask_b32_e32 v124, v124, v204, vcc
	ds_write_b32 v177, v124 offset:16
.LBB0_89:
	s_or_b64 exec, exec, s[0:1]
	v_add_f32_e32 v122, v122, v123
	v_add_f32_e32 v120, v120, v121
	v_cndmask_b32_e64 v124, v148, v149, s[74:75]
	v_add_f32_e32 v120, v120, v122
	v_add_f32_e32 v120, v120, v124
	s_waitcnt lgkmcnt(0)
	s_nop 0
	v_add_f32_dpp v120, v120, v120 quad_perm:[1,0,3,2] row_mask:0xf bank_mask:0xf
	s_nop 1
	v_add_f32_dpp v120, v120, v120 quad_perm:[2,3,0,1] row_mask:0xf bank_mask:0xf
	s_and_saveexec_b64 s[0:1], s[12:13]
	s_cbranch_execz .LBB0_91
	v_cmp_eq_u32_e32 vcc, s89, v180
	v_cmp_eq_u32_e64 s[78:79], s3, v180
	v_cmp_ge_i32_e64 s[80:81], s89, v180
	s_or_b64 vcc, vcc, s[78:79]
	s_nop 0
	v_cndmask_b32_e64 v120, v252, v120, s[80:81]
	v_cndmask_b32_e32 v120, v120, v204, vcc
	ds_write_b32 v177, v120 offset:24
.LBB0_91:
	s_or_b64 exec, exec, s[0:1]
	v_add_f32_e32 v94, v94, v95
	v_add_f32_e32 v92, v92, v93
	v_cndmask_b32_e64 v120, v147, v148, s[74:75]
	v_add_f32_e32 v92, v92, v94
	v_add_f32_e32 v92, v92, v120
	s_waitcnt lgkmcnt(0)
	s_nop 0
	v_add_f32_dpp v92, v92, v92 quad_perm:[1,0,3,2] row_mask:0xf bank_mask:0xf
	s_nop 1
	v_add_f32_dpp v92, v92, v92 quad_perm:[2,3,0,1] row_mask:0xf bank_mask:0xf
	s_and_saveexec_b64 s[0:1], s[12:13]
	s_cbranch_execz .LBB0_93
	v_cmp_eq_u32_e32 vcc, s89, v181
	v_cmp_eq_u32_e64 s[78:79], s3, v181
	v_cmp_ge_i32_e64 s[80:81], s89, v181
	s_or_b64 vcc, vcc, s[78:79]
	s_nop 0
	v_cndmask_b32_e64 v92, v252, v92, s[80:81]
	v_cndmask_b32_e32 v92, v92, v204, vcc
	ds_write_b32 v177, v92 offset:32
.LBB0_93:
	s_or_b64 exec, exec, s[0:1]
	v_add_f32_e32 v90, v90, v91
	v_add_f32_e32 v88, v88, v89
	v_cndmask_b32_e64 v92, v146, v147, s[74:75]
	v_add_f32_e32 v88, v88, v90
	v_add_f32_e32 v88, v88, v92
	s_waitcnt lgkmcnt(0)
	s_nop 0
	v_add_f32_dpp v88, v88, v88 quad_perm:[1,0,3,2] row_mask:0xf bank_mask:0xf
	s_nop 1
	v_add_f32_dpp v88, v88, v88 quad_perm:[2,3,0,1] row_mask:0xf bank_mask:0xf
	s_and_saveexec_b64 s[0:1], s[12:13]
	s_cbranch_execz .LBB0_95
	v_cmp_eq_u32_e32 vcc, s89, v182
	v_cmp_eq_u32_e64 s[78:79], s3, v182
	v_cmp_ge_i32_e64 s[80:81], s89, v182
	s_or_b64 vcc, vcc, s[78:79]
	s_nop 0
	v_cndmask_b32_e64 v88, v252, v88, s[80:81]
	v_cndmask_b32_e32 v88, v88, v204, vcc
	ds_write_b32 v177, v88 offset:40
.LBB0_95:
	s_or_b64 exec, exec, s[0:1]
	v_add_f32_e32 v86, v86, v87
	v_add_f32_e32 v84, v84, v85
	v_cndmask_b32_e64 v88, v145, v146, s[74:75]
	v_add_f32_e32 v84, v84, v86
	v_add_f32_e32 v84, v84, v88
	s_waitcnt lgkmcnt(0)
	s_nop 0
	v_add_f32_dpp v84, v84, v84 quad_perm:[1,0,3,2] row_mask:0xf bank_mask:0xf
	s_nop 1
	v_add_f32_dpp v84, v84, v84 quad_perm:[2,3,0,1] row_mask:0xf bank_mask:0xf
	s_and_saveexec_b64 s[0:1], s[12:13]
	s_cbranch_execz .LBB0_97
	v_cmp_eq_u32_e32 vcc, s89, v183
	v_cmp_eq_u32_e64 s[78:79], s3, v183
	v_cmp_ge_i32_e64 s[80:81], s89, v183
	s_or_b64 vcc, vcc, s[78:79]
	s_nop 0
	v_cndmask_b32_e64 v84, v252, v84, s[80:81]
	v_cndmask_b32_e32 v84, v84, v204, vcc
	ds_write_b32 v177, v84 offset:48
.LBB0_97:
	s_or_b64 exec, exec, s[0:1]
	v_add_f32_e32 v82, v82, v83
	v_add_f32_e32 v80, v80, v81
	v_cndmask_b32_e64 v84, v144, v145, s[74:75]
	v_add_f32_e32 v80, v80, v82
	v_add_f32_e32 v80, v80, v84
	s_waitcnt lgkmcnt(0)
	s_nop 0
	v_add_f32_dpp v80, v80, v80 quad_perm:[1,0,3,2] row_mask:0xf bank_mask:0xf
	s_nop 1
	v_add_f32_dpp v80, v80, v80 quad_perm:[2,3,0,1] row_mask:0xf bank_mask:0xf
	s_and_saveexec_b64 s[0:1], s[12:13]
	s_cbranch_execz .LBB0_99
	v_cmp_eq_u32_e32 vcc, s89, v184
	v_cmp_eq_u32_e64 s[78:79], s3, v184
	v_cmp_ge_i32_e64 s[80:81], s89, v184
	s_or_b64 vcc, vcc, s[78:79]
	s_nop 0
	v_cndmask_b32_e64 v80, v252, v80, s[80:81]
	v_cndmask_b32_e32 v80, v80, v204, vcc
	ds_write_b32 v177, v80 offset:56
.LBB0_99:
	s_or_b64 exec, exec, s[0:1]
	v_add_f32_e32 v62, v62, v63
	v_add_f32_e32 v60, v60, v61
	v_cndmask_b32_e64 v80, v143, v144, s[74:75]
	v_add_f32_e32 v60, v60, v62
	v_add_f32_e32 v60, v60, v80
	s_waitcnt lgkmcnt(0)
	s_nop 0
	v_add_f32_dpp v60, v60, v60 quad_perm:[1,0,3,2] row_mask:0xf bank_mask:0xf
	s_nop 1
	v_add_f32_dpp v60, v60, v60 quad_perm:[2,3,0,1] row_mask:0xf bank_mask:0xf
	s_and_saveexec_b64 s[0:1], s[12:13]
	s_cbranch_execz .LBB0_101
	v_cmp_eq_u32_e32 vcc, s89, v185
	v_cmp_eq_u32_e64 s[78:79], s3, v185
	v_cmp_ge_i32_e64 s[80:81], s89, v185
	s_or_b64 vcc, vcc, s[78:79]
	s_nop 0
	v_cndmask_b32_e64 v60, v252, v60, s[80:81]
	v_cndmask_b32_e32 v60, v60, v204, vcc
	ds_write_b32 v177, v60 offset:64
.LBB0_101:
	s_or_b64 exec, exec, s[0:1]
	v_add_f32_e32 v58, v58, v59
	v_add_f32_e32 v56, v56, v57
	v_cndmask_b32_e64 v60, v142, v143, s[74:75]
	v_add_f32_e32 v56, v56, v58
	v_add_f32_e32 v56, v56, v60
	s_waitcnt lgkmcnt(0)
	s_nop 0
	v_add_f32_dpp v56, v56, v56 quad_perm:[1,0,3,2] row_mask:0xf bank_mask:0xf
	s_nop 1
	v_add_f32_dpp v56, v56, v56 quad_perm:[2,3,0,1] row_mask:0xf bank_mask:0xf
	s_and_saveexec_b64 s[0:1], s[12:13]
	s_cbranch_execz .LBB0_103
	v_cmp_eq_u32_e32 vcc, s89, v186
	v_cmp_eq_u32_e64 s[78:79], s3, v186
	v_cmp_ge_i32_e64 s[80:81], s89, v186
	s_or_b64 vcc, vcc, s[78:79]
	s_nop 0
	v_cndmask_b32_e64 v56, v252, v56, s[80:81]
	v_cndmask_b32_e32 v56, v56, v204, vcc
	ds_write_b32 v177, v56 offset:72
.LBB0_103:
	s_or_b64 exec, exec, s[0:1]
	v_add_f32_e32 v54, v54, v55
	v_add_f32_e32 v52, v52, v53
	v_cndmask_b32_e64 v56, v141, v142, s[74:75]
	v_add_f32_e32 v52, v52, v54
	v_add_f32_e32 v52, v52, v56
	s_waitcnt lgkmcnt(0)
	s_nop 0
	v_add_f32_dpp v52, v52, v52 quad_perm:[1,0,3,2] row_mask:0xf bank_mask:0xf
	s_nop 1
	v_add_f32_dpp v52, v52, v52 quad_perm:[2,3,0,1] row_mask:0xf bank_mask:0xf
	s_and_saveexec_b64 s[0:1], s[12:13]
	s_cbranch_execz .LBB0_105
	v_cmp_eq_u32_e32 vcc, s89, v187
	v_cmp_eq_u32_e64 s[78:79], s3, v187
	v_cmp_ge_i32_e64 s[80:81], s89, v187
	s_or_b64 vcc, vcc, s[78:79]
	s_nop 0
	v_cndmask_b32_e64 v52, v252, v52, s[80:81]
	v_cndmask_b32_e32 v52, v52, v204, vcc
	ds_write_b32 v177, v52 offset:80
.LBB0_105:
	s_or_b64 exec, exec, s[0:1]
	v_add_f32_e32 v50, v50, v51
	v_add_f32_e32 v48, v48, v49
	v_cndmask_b32_e64 v52, v140, v141, s[74:75]
	v_add_f32_e32 v48, v48, v50
	v_add_f32_e32 v48, v48, v52
	s_waitcnt lgkmcnt(0)
	s_nop 0
	v_add_f32_dpp v48, v48, v48 quad_perm:[1,0,3,2] row_mask:0xf bank_mask:0xf
	s_nop 1
	v_add_f32_dpp v48, v48, v48 quad_perm:[2,3,0,1] row_mask:0xf bank_mask:0xf
	s_and_saveexec_b64 s[0:1], s[12:13]
	s_cbranch_execz .LBB0_107
	v_cmp_eq_u32_e32 vcc, s89, v188
	v_cmp_eq_u32_e64 s[78:79], s3, v188
	v_cmp_ge_i32_e64 s[80:81], s89, v188
	s_or_b64 vcc, vcc, s[78:79]
	s_nop 0
	v_cndmask_b32_e64 v48, v252, v48, s[80:81]
	v_cndmask_b32_e32 v48, v48, v204, vcc
	ds_write_b32 v177, v48 offset:88
.LBB0_107:
	s_or_b64 exec, exec, s[0:1]
	v_add_f32_e32 v46, v46, v47
	v_add_f32_e32 v44, v44, v45
	v_cndmask_b32_e64 v48, v139, v140, s[74:75]
	v_add_f32_e32 v44, v44, v46
	v_add_f32_e32 v44, v44, v48
	s_waitcnt lgkmcnt(0)
	s_nop 0
	v_add_f32_dpp v44, v44, v44 quad_perm:[1,0,3,2] row_mask:0xf bank_mask:0xf
	s_nop 1
	v_add_f32_dpp v44, v44, v44 quad_perm:[2,3,0,1] row_mask:0xf bank_mask:0xf
	s_and_saveexec_b64 s[0:1], s[12:13]
	s_cbranch_execz .LBB0_109
	v_cmp_eq_u32_e32 vcc, s89, v189
	v_cmp_eq_u32_e64 s[78:79], s3, v189
	v_cmp_ge_i32_e64 s[80:81], s89, v189
	s_or_b64 vcc, vcc, s[78:79]
	s_nop 0
	v_cndmask_b32_e64 v44, v252, v44, s[80:81]
	v_cndmask_b32_e32 v44, v44, v204, vcc
	ds_write_b32 v177, v44 offset:96
.LBB0_109:
	s_or_b64 exec, exec, s[0:1]
	v_add_f32_e32 v42, v42, v43
	v_add_f32_e32 v40, v40, v41
	v_cndmask_b32_e64 v44, v138, v139, s[74:75]
	v_add_f32_e32 v40, v40, v42
	v_add_f32_e32 v40, v40, v44
	s_waitcnt lgkmcnt(0)
	s_nop 0
	v_add_f32_dpp v40, v40, v40 quad_perm:[1,0,3,2] row_mask:0xf bank_mask:0xf
	s_nop 1
	v_add_f32_dpp v40, v40, v40 quad_perm:[2,3,0,1] row_mask:0xf bank_mask:0xf
	s_and_saveexec_b64 s[0:1], s[12:13]
	s_cbranch_execz .LBB0_111
	v_cmp_eq_u32_e32 vcc, s89, v190
	v_cmp_eq_u32_e64 s[78:79], s3, v190
	v_cmp_ge_i32_e64 s[80:81], s89, v190
	s_or_b64 vcc, vcc, s[78:79]
	s_nop 0
	v_cndmask_b32_e64 v40, v252, v40, s[80:81]
	v_cndmask_b32_e32 v40, v40, v204, vcc
	ds_write_b32 v177, v40 offset:104
.LBB0_111:
	s_or_b64 exec, exec, s[0:1]
	v_add_f32_e32 v38, v38, v39
	v_add_f32_e32 v36, v36, v37
	v_cndmask_b32_e64 v40, v119, v138, s[74:75]
	v_add_f32_e32 v36, v36, v38
	v_add_f32_e32 v36, v36, v40
	s_waitcnt lgkmcnt(0)
	s_nop 0
	v_add_f32_dpp v36, v36, v36 quad_perm:[1,0,3,2] row_mask:0xf bank_mask:0xf
	s_nop 1
	v_add_f32_dpp v36, v36, v36 quad_perm:[2,3,0,1] row_mask:0xf bank_mask:0xf
	s_and_saveexec_b64 s[0:1], s[12:13]
	s_cbranch_execz .LBB0_113
	v_cmp_eq_u32_e32 vcc, s89, v191
	v_cmp_eq_u32_e64 s[78:79], s3, v191
	v_cmp_ge_i32_e64 s[80:81], s89, v191
	s_or_b64 vcc, vcc, s[78:79]
	s_nop 0
	v_cndmask_b32_e64 v36, v252, v36, s[80:81]
	v_cndmask_b32_e32 v36, v36, v204, vcc
	ds_write_b32 v177, v36 offset:112
.LBB0_113:
	s_or_b64 exec, exec, s[0:1]
	v_add_f32_e32 v34, v34, v35
	v_add_f32_e32 v32, v32, v33
	v_cndmask_b32_e64 v36, v136, v119, s[74:75]
	v_add_f32_e32 v32, v32, v34
	v_add_f32_e32 v32, v32, v36
	s_waitcnt lgkmcnt(0)
	s_nop 0
	v_add_f32_dpp v32, v32, v32 quad_perm:[1,0,3,2] row_mask:0xf bank_mask:0xf
	s_nop 1
	v_add_f32_dpp v32, v32, v32 quad_perm:[2,3,0,1] row_mask:0xf bank_mask:0xf
	s_and_saveexec_b64 s[0:1], s[12:13]
	s_cbranch_execz .LBB0_115
	v_cmp_eq_u32_e32 vcc, s89, v192
	v_cmp_eq_u32_e64 s[78:79], s3, v192
	v_cmp_ge_i32_e64 s[80:81], s89, v192
	s_or_b64 vcc, vcc, s[78:79]
	s_nop 0
	v_cndmask_b32_e64 v32, v252, v32, s[80:81]
	v_cndmask_b32_e32 v32, v32, v204, vcc
	ds_write_b32 v177, v32 offset:120

.LBB0_143:
	v_add_u32_e32 v32, v114, v160
	v_ashrrev_i32_e32 v33, 31, v32
	v_lshlrev_b64 v[32:33], 12, v[32:33]
	v_lshl_add_u64 v[72:73], v[92:93], 0, v[32:33]
	global_load_dwordx4 v[32:35], v[72:73], off offset:2048
	global_load_dwordx4 v[64:67], v[72:73], off offset:2080
	global_load_dwordx4 v[68:71], v[72:73], off offset:2112
	global_load_dwordx4 v[94:97], v[72:73], off offset:2144
	v_lshl_add_u64 v[76:77], v[160:161], 1, v[90:91]
	s_mov_b32 s38, 0x100000
	s_waitcnt vmcnt(3)
	v_mfma_f32_32x32x16_bf16 v[32:47], v[32:35], v[48:51], 0
	s_waitcnt vmcnt(2)
	v_mfma_f32_32x32x16_bf16 v[32:47], v[64:67], v[52:55], v[32:47]
	global_load_dwordx2 v[72:73], v[76:77], off
	global_load_dwordx2 v[74:75], v[76:77], off offset:16
	global_load_dwordx2 v[64:65], v[76:77], off offset:32
	global_load_dwordx2 v[66:67], v[76:77], off offset:48
	s_waitcnt vmcnt(5)
	v_mfma_f32_32x32x16_bf16 v[32:47], v[68:71], v[56:59], v[32:47]
	v_add_co_u32_e64 v70, s[38:39], s38, v76
	s_nop 1
	v_addc_co_u32_e64 v71, s[38:39], 0, v77, s[38:39]
	global_load_dwordx2 v[76:77], v[70:71], off
	global_load_dwordx2 v[78:79], v[70:71], off offset:16
	global_load_dwordx2 v[68:69], v[70:71], off offset:32
	s_nop 0
	global_load_dwordx2 v[70:71], v[70:71], off offset:48
	v_cmp_eq_u32_e64 s[38:39], v85, v160
	s_waitcnt vmcnt(8)
	v_mfma_f32_32x32x16_bf16 v[32:47], v[94:97], v[60:63], v[32:47]
	s_nop 11
	v_exp_f32_e32 v32, v32
	v_exp_f32_e32 v33, v33
	v_exp_f32_e32 v34, v34
	v_exp_f32_e32 v35, v35
	v_exp_f32_e32 v94, v36
	v_exp_f32_e32 v95, v37
	v_exp_f32_e32 v38, v38
	v_exp_f32_e32 v39, v39
	v_exp_f32_e32 v40, v40
	v_exp_f32_e32 v41, v41
	v_exp_f32_e32 v42, v42
	v_exp_f32_e32 v43, v43
	v_exp_f32_e32 v96, v44
	v_exp_f32_e32 v97, v45
	v_exp_f32_e32 v46, v46
	v_exp_f32_e32 v47, v47
	v_min_f32_e32 v36, 0x7149f2ca, v32
	v_min_f32_e32 v37, 0x7149f2ca, v33
	v_min_f32_e32 v32, 0x7149f2ca, v34
	v_min_f32_e32 v100, 0x7149f2ca, v35
	v_min_f32_e32 v44, 0x7149f2ca, v94
	v_min_f32_e32 v45, 0x7149f2ca, v95
	v_min_f32_e32 v38, 0x7149f2ca, v38
	v_min_f32_e32 v104, 0x7149f2ca, v39
	v_min_f32_e32 v116, 0x7149f2ca, v40
	v_min_f32_e32 v117, 0x7149f2ca, v41
	v_min_f32_e32 v40, 0x7149f2ca, v42
	v_min_f32_e32 v42, 0x7149f2ca, v43
	v_min_f32_e32 v124, 0x7149f2ca, v96
	v_min_f32_e32 v125, 0x7149f2ca, v97
	v_min_f32_e32 v106, 0x7149f2ca, v46
	v_min_f32_e32 v108, 0x7149f2ca, v47
	v_add_f32_e32 v33, 1.0, v36
	v_add_f32_e32 v34, 1.0, v37
	v_add_f32_e32 v35, 1.0, v32
	v_add_f32_e32 v39, 1.0, v100
	v_add_f32_e32 v41, 1.0, v44
	v_add_f32_e32 v94, 1.0, v45
	v_add_f32_e32 v95, 1.0, v38
	v_add_f32_e32 v98, 1.0, v104
	v_add_f32_e32 v99, 1.0, v116
	v_add_f32_e32 v103, 1.0, v117
	v_add_f32_e32 v107, 1.0, v40
	v_add_f32_e32 v109, 1.0, v42
	v_add_f32_e32 v118, 1.0, v124
	v_add_f32_e32 v119, 1.0, v125
	v_add_f32_e32 v120, 1.0, v106
	v_add_f32_e32 v121, 1.0, v108
	v_rcp_f32_e32 v46, v33
	v_rcp_f32_e32 v47, v34
	v_rcp_f32_e32 v101, v35
	v_rcp_f32_e32 v43, v39
	v_rcp_f32_e32 v96, v41
	v_rcp_f32_e32 v97, v94
	v_rcp_f32_e32 v105, v95
	v_rcp_f32_e32 v41, v98
	v_rcp_f32_e32 v102, v99
	v_rcp_f32_e32 v103, v103
	v_rcp_f32_e32 v107, v107
	v_rcp_f32_e32 v39, v109
	v_rcp_f32_e32 v34, v118
	v_rcp_f32_e32 v35, v119
	v_rcp_f32_e32 v109, v120
	v_rcp_f32_e32 v33, v121
	v_pk_mul_f32 v[98:99], v[36:37], v[46:47]
	v_mul_f32_e32 v123, v32, v101
	v_mul_f32_e32 v122, v100, v43
	v_pk_mul_f32 v[94:95], v[44:45], v[96:97]
	v_mul_f32_e32 v120, v38, v105
	v_mul_f32_e32 v121, v104, v41
	v_pk_mul_f32 v[44:45], v[116:117], v[102:103]
	v_mul_f32_e32 v118, v40, v107
	v_mul_f32_e32 v119, v42, v39
	v_pk_mul_f32 v[36:37], v[124:125], v[34:35]
	v_mul_f32_e32 v116, v106, v109
	v_mul_f32_e32 v117, v108, v33
	s_and_saveexec_b64 s[44:45], s[38:39]
	s_cbranch_execz .LBB0_142
	v_cndmask_b32_e64 v46, 1.0, v46, s[4:5]
	v_cndmask_b32_e64 v47, 1.0, v47, s[6:7]
	v_cndmask_b32_e64 v99, 0, v99, s[6:7]
	v_cndmask_b32_e64 v98, 0, v98, s[4:5]
	v_cndmask_b32_e64 v101, 1.0, v101, s[8:9]
	v_cndmask_b32_e64 v123, 0, v123, s[8:9]
	v_cndmask_b32_e64 v43, 1.0, v43, s[10:11]
	v_cndmask_b32_e64 v122, 0, v122, s[10:11]
	v_cndmask_b32_e64 v96, 1.0, v96, s[14:15]
	v_cndmask_b32_e64 v97, 1.0, v97, s[12:13]
	v_cndmask_b32_e64 v95, 0, v95, s[12:13]
	v_cndmask_b32_e64 v94, 0, v94, s[14:15]
	v_cndmask_b32_e64 v105, 1.0, v105, s[16:17]
	v_cndmask_b32_e64 v120, 0, v120, s[16:17]
	v_cndmask_b32_e64 v41, 1.0, v41, s[18:19]
	v_cndmask_b32_e64 v121, 0, v121, s[18:19]
	v_cndmask_b32_e64 v102, 1.0, v102, s[22:23]
	v_cndmask_b32_e64 v103, 1.0, v103, s[20:21]
	v_cndmask_b32_e64 v45, 0, v45, s[20:21]
	v_cndmask_b32_e64 v44, 0, v44, s[22:23]
	v_cndmask_b32_e64 v107, 1.0, v107, s[24:25]
	v_cndmask_b32_e64 v118, 0, v118, s[24:25]
	v_cndmask_b32_e64 v39, 1.0, v39, s[26:27]
	v_cndmask_b32_e64 v119, 0, v119, s[26:27]
	v_cndmask_b32_e64 v34, 1.0, v34, s[30:31]
	v_cndmask_b32_e64 v35, 1.0, v35, s[28:29]
	v_cndmask_b32_e64 v37, 0, v37, s[28:29]
	v_cndmask_b32_e64 v36, 0, v36, s[30:31]
	v_cndmask_b32_e64 v109, 1.0, v109, s[34:35]
	v_cndmask_b32_e64 v116, 0, v116, s[34:35]
	v_cndmask_b32_e64 v33, 1.0, v33, s[36:37]
	v_cndmask_b32_e64 v117, 0, v117, s[36:37]
	s_branch .LBB0_142
	s_nop 0
	s_nop 0
	s_nop 0
	s_nop 0
	s_nop 0
	s_nop 0
	s_nop 0
	s_nop 0
	s_nop 0
	s_nop 0
	s_nop 0
	s_nop 0
	s_nop 0
	s_nop 0
	s_nop 0
